# v88 + lazy conversion of FFN-gate L3 weights (id 7) moved from the QKV phase (ph11) to the FFN-up phase ph9 (rebalanced conversion sets)
# speedup vs baseline: 1.0033x; 1.0017x over previous
.LBB0_31:
	s_andn2_b64 vcc, exec, s[2:3]
	v_readlane_b32 s2, v209, 28
	v_readlane_b32 s76, v209, 22
	v_readlane_b32 s26, v209, 24
	v_readlane_b32 s3, v209, 29
	v_readlane_b32 s77, v209, 23
	v_readlane_b32 s27, v209, 25
	v_writelane_b32 v209, s2, 26
	s_nop 1
	v_writelane_b32 v209, s3, 27
	s_cbranch_vccnz .LBB0_403
	v_readlane_b32 s3, v209, 42
	s_add_i32 s0, s3, -1
	s_mul_hi_i32 s1, s0, 0x66666667
	s_lshr_b32 s2, s1, 31
	s_ashr_i32 s1, s1, 1
	s_add_i32 s84, s1, s2
	s_ashr_i32 s85, s84, 31
	s_mul_i32 s2, s84, 0x1600000
	v_readlane_b32 s4, v209, 38
	s_mul_hi_i32 s1, s84, 0x1600000
	v_readlane_b32 s5, v209, 39
	s_add_u32 s4, s4, s2
	s_addc_u32 s5, s5, s1
	v_writelane_b32 v209, s4, 43
	s_mul_i32 s1, s84, 5
	s_mov_b64 s[6:7], -1
	v_writelane_b32 v209, s5, 44
	s_sub_i32 s4, s0, s1
	s_add_u32 s16, s18, 0x15e00000
	s_addc_u32 s17, s19, 0
	s_add_u32 s82, s18, 0x19e00000
	s_addc_u32 s83, s19, 0
	s_add_u32 s34, s18, 0x1be00000
	s_addc_u32 s35, s19, 0
	s_add_u32 s0, s18, 0x1de00000
	s_addc_u32 s1, s19, 0
	s_add_i32 s2, s84, -2
	v_writelane_b32 v209, s0, 45
	s_cmp_gt_i32 s3, 10
	s_mov_b64 s[10:11], 0
	v_writelane_b32 v209, s1, 46
	s_cselect_b64 s[0:1], -1, 0
	v_writelane_b32 v209, s0, 47
	s_nop 1
	v_writelane_b32 v209, s1, 48
	s_mov_b32 s0, s2
	v_writelane_b32 v209, s0, 49
	s_nop 1
	v_writelane_b32 v209, s1, 50
	s_lshl_b32 s0, s2, 11
	s_ashr_i32 s1, s0, 31
	v_writelane_b32 v209, s0, 51
	s_mov_b64 s[2:3], 0
	s_cmp_lt_i32 s4, 2
	v_writelane_b32 v209, s1, 52
	v_writelane_b32 v209, s4, 53
	v_writelane_b32 v209, s2, 54
	s_nop 1
	v_writelane_b32 v209, s3, 55
	s_cbranch_scc1 .LBB0_128
	v_readlane_b32 s2, v209, 53
	s_mov_b64 s[0:1], -1
	s_mov_b64 s[8:9], 0
	s_cmp_gt_i32 s2, 2
	s_mov_b64 s[2:3], 0
	s_cbranch_scc0 .LBB0_124
	v_readlane_b32 s0, v209, 53
	s_cmp_eq_u32 s0, 3
	s_mov_b64 s[2:3], -1
	s_cbranch_scc0 .LBB0_123
	v_readlane_b32 s0, v253, 63
	v_readlane_b32 s1, v254, 0
	s_andn2_b64 vcc, exec, s[0:1]
	v_readlane_b32 s20, v254, 1
	s_cbranch_vccnz .LBB0_84
	v_readlane_b32 s2, v209, 42
	s_add_i32 s0, s2, 3
	s_add_i32 s1, s2, -6
	s_add_i32 s2, s2, -11
	s_cmp_lt_u32 s2, 5
	s_mov_b32 s2, 0x1f5d24e
	s_cselect_b32 s2, s2, 0x3ef
	s_cmp_gt_u32 s1, 4
	v_mov_b32_e32 v0, v234
	s_cselect_b32 s1, s2, 0x3e79c22d
	s_cmp_gt_u32 s0, 8
	s_cselect_b32 s26, s1, 0x3e548c2c
	v_readfirstlane_b32 s3, v0
	s_lshr_b32 s3, s3, 6
	v_lshlrev_b32_e32 v1, 2, v0
	s_mulk_i32 s3, 0x4100
	v_bfe_u32 v9, v0, 4, 2
	v_and_b32_e32 v8, 60, v1
	s_add_i32 s3, s3, 0
	v_lshlrev_b32_e32 v1, 2, v8
	v_mul_u32_u24_e32 v2, 0x104, v9
	v_add3_u32 v11, s3, v1, v2
	v_and_b32_e32 v1, 7, v0
	v_readlane_b32 s4, v209, 30
	v_lshlrev_b32_e32 v204, 4, v1
	v_readlane_b32 s5, v209, 31
	v_readfirstlane_b32 s0, v234
	v_bfe_u32 v78, v0, 3, 3
	v_lshl_add_u64 v[12:13], s[4:5], 0, v[204:205]
	v_readlane_b32 s4, v209, 38
	v_readlane_b32 s5, v209, 39
	s_mov_b32 s27, 0
	s_lshr_b32 s2, s0, 6
	v_lshl_add_u64 v[14:15], s[4:5], 0, v[204:205]
	v_readlane_b32 s4, v209, 32
	v_readlane_b32 s5, v209, 33
	v_readlane_b32 s0, v254, 4
	v_lshlrev_b32_e32 v10, 3, v1
	v_lshl_add_u64 v[16:17], s[4:5], 0, v[204:205]
	v_readlane_b32 s4, v209, 36
	v_readlane_b32 s5, v209, 37
	v_mul_u32_u24_e32 v0, 0x820, v1
	v_lshlrev_b32_e32 v1, 2, v78
	v_lshl_add_u64 v[20:21], s[4:5], 0, v[204:205]
	v_readlane_b32 s4, v209, 34
	v_readlane_b32 s5, v209, 35
	s_add_i32 s2, s2, s0
	s_and_b32 s0, s26, 15
	v_lshl_add_u64 v[22:23], s[4:5], 0, v[204:205]
	v_readlane_b32 s4, v209, 40
	v_readlane_b32 s5, v209, 41
	s_mov_b32 s1, s27
	v_add3_u32 v79, s3, v0, v1
	v_or_b32_e32 v80, 8, v78
	v_or_b32_e32 v81, 16, v78
	v_or_b32_e32 v82, 24, v78
	v_or_b32_e32 v83, 32, v78
	v_or_b32_e32 v84, 40, v78
	v_or_b32_e32 v85, 48, v78
	v_or_b32_e32 v86, 56, v78
	v_lshl_add_u64 v[18:19], s[18:19], 0, v[204:205]
	v_lshl_add_u64 v[24:25], s[4:5], 0, v[204:205]
	s_mov_b32 s3, s27
	s_branch .LBB0_38

.LBB0_233:
	s_and_b64 vcc, exec, s[10:11]
	s_cbranch_vccz .LBB0_402
	v_readlane_b32 s2, v209, 47
	v_readlane_b32 s3, v209, 48
	s_mov_b64 s[0:1], -1
	s_and_b64 vcc, exec, s[2:3]
	s_cbranch_vccz .LBB0_327
	v_readlane_b32 s0, v209, 49
	s_cmp_eq_u32 s0, 0
	s_cselect_b64 s[2:3], -1, 0
	s_cmp_lg_u32 s0, 0
	v_readlane_b32 s1, v209, 50
	s_cbranch_scc1 .LBB0_286
	v_readlane_b32 s0, v254, 10
	v_readlane_b32 s1, v254, 11
	s_andn2_b64 vcc, exec, s[0:1]
	s_cbranch_vccnz .LBB0_285
	v_readfirstlane_b32 s0, v234
	s_lshr_b32 s28, s0, 6
	v_readlane_b32 s0, v254, 15
	v_mov_b32_e32 v0, v234
	s_add_i32 s28, s28, s0
	v_readlane_b32 s4, v209, 30
	v_readfirstlane_b32 s0, v0
	s_lshr_b32 s0, s0, 6
	v_lshlrev_b32_e32 v1, 2, v0
	s_mulk_i32 s0, 0x4100
	v_bfe_u32 v9, v0, 4, 2
	v_and_b32_e32 v8, 60, v1
	s_add_i32 s0, s0, 0
	v_lshlrev_b32_e32 v1, 2, v8
	v_mul_u32_u24_e32 v2, 0x104, v9
	v_add3_u32 v11, s0, v1, v2
	v_and_b32_e32 v1, 7, v0
	v_bfe_u32 v78, v0, 3, 3
	v_lshlrev_b32_e32 v10, 3, v1
	v_mul_u32_u24_e32 v0, 0x820, v1
	v_lshlrev_b32_e32 v204, 4, v1
	v_lshlrev_b32_e32 v1, 2, v78
	v_add3_u32 v79, s0, v0, v1
	v_readlane_b32 s0, v209, 38
	v_readlane_b32 s1, v209, 39
	v_readlane_b32 s5, v209, 31
	v_or_b32_e32 v80, 8, v78
	v_lshl_add_u64 v[14:15], s[0:1], 0, v[204:205]
	v_readlane_b32 s0, v209, 32
	v_readlane_b32 s1, v209, 33
	v_lshl_add_u64 v[12:13], s[4:5], 0, v[204:205]
	v_or_b32_e32 v81, 16, v78
	v_lshl_add_u64 v[16:17], s[0:1], 0, v[204:205]
	v_readlane_b32 s0, v209, 36
	v_readlane_b32 s1, v209, 37
	v_or_b32_e32 v82, 24, v78
	v_or_b32_e32 v83, 32, v78
	v_lshl_add_u64 v[20:21], s[0:1], 0, v[204:205]
	v_readlane_b32 s0, v209, 34
	v_readlane_b32 s1, v209, 35
	v_or_b32_e32 v84, 40, v78
	v_or_b32_e32 v85, 48, v78
	v_lshl_add_u64 v[22:23], s[0:1], 0, v[204:205]
	v_readlane_b32 s0, v209, 40
	v_readlane_b32 s1, v209, 41
	v_or_b32_e32 v86, 56, v78
	v_lshl_add_u64 v[18:19], s[18:19], 0, v[204:205]
	v_lshl_add_u64 v[24:25], s[0:1], 0, v[204:205]
	s_mov_b32 s29, 0
	s_mov_b32 s8, 0x7d46
	s_mov_b32 s9, 0x0
	s_mov_b64 s[0:1], 6
	s_branch .LBB0_239

.LBB0_403:
	s_and_b64 vcc, exec, s[0:1]
	s_cbranch_vccz .LBB0_458
	v_mov_b32_e32 v9, v234
	v_readlane_b32 s1, v252, 15
	v_readfirstlane_b32 s0, v9
	s_ashr_i32 s0, s0, 6
	v_mov_b32_e32 v0, v234
	s_add_i32 s2, s0, s1
	s_waitcnt lgkmcnt(0)
	v_readlane_b32 s4, v209, 30
	v_readfirstlane_b32 s0, v0
	s_lshr_b32 s0, s0, 6
	v_lshlrev_b32_e32 v1, 2, v0
	s_mulk_i32 s0, 0x4100
	v_bfe_u32 v11, v0, 4, 2
	v_and_b32_e32 v8, 60, v1
	s_add_i32 s0, s0, 0
	v_lshlrev_b32_e32 v1, 2, v8
	v_mul_u32_u24_e32 v2, 0x104, v11
	v_add3_u32 v78, s0, v1, v2
	v_and_b32_e32 v1, 7, v0
	v_bfe_u32 v79, v0, 3, 3
	v_lshlrev_b32_e32 v10, 3, v1
	v_mul_u32_u24_e32 v0, 0x820, v1
	v_lshlrev_b32_e32 v204, 4, v1
	v_lshlrev_b32_e32 v1, 2, v79
	v_add3_u32 v80, s0, v0, v1
	v_readlane_b32 s0, v209, 38
	v_readlane_b32 s1, v209, 39
	v_readlane_b32 s5, v209, 31
	v_or_b32_e32 v81, 8, v79
	v_lshl_add_u64 v[14:15], s[0:1], 0, v[204:205]
	v_readlane_b32 s0, v209, 32
	v_readlane_b32 s1, v209, 33
	v_lshl_add_u64 v[12:13], s[4:5], 0, v[204:205]
	v_or_b32_e32 v82, 16, v79
	v_lshl_add_u64 v[16:17], s[0:1], 0, v[204:205]
	v_readlane_b32 s0, v209, 36
	v_readlane_b32 s1, v209, 37
	v_or_b32_e32 v83, 24, v79
	v_or_b32_e32 v84, 32, v79
	v_lshl_add_u64 v[20:21], s[0:1], 0, v[204:205]
	v_readlane_b32 s0, v209, 34
	v_readlane_b32 s1, v209, 35
	v_or_b32_e32 v85, 40, v79
	v_or_b32_e32 v86, 48, v79
	v_lshl_add_u64 v[22:23], s[0:1], 0, v[204:205]
	v_readlane_b32 s0, v209, 40
	v_readlane_b32 s1, v209, 41
	v_or_b32_e32 v87, 56, v79
	v_lshl_add_u64 v[18:19], s[18:19], 0, v[204:205]
	v_lshl_add_u64 v[24:25], s[0:1], 0, v[204:205]
	s_mov_b32 s3, 0
	s_mov_b32 s8, 0x1f41040
	s_mov_b32 s9, 0x0
	s_mov_b64 s[0:1], 0
	s_branch .LBB0_406
